# write-through (sc1) epilogue stores in P2/P5/P9 GEMMs so the barrier L2 writeback has less to flush
# baseline (speedup 1.0000x reference)
.LBB0_216:
	v_lshl_add_u32 v150, s41, 8, v140
	v_lshl_or_b32 v144, s40, 8, v142
	v_ashrrev_i32_e32 v145, 31, v144
	v_mov_b64_e32 v[146:147], s[4:5]
	v_cvt_pk_bf16_f32 v70, v70, v71
	v_cvt_pk_bf16_f32 v71, v72, v73
	v_cvt_pk_bf16_f32 v72, v66, v67
	v_add_u32_e32 v66, 0x80, v150
	v_mad_i64_i32 v[148:149], s[18:19], v150, s33, v[146:147]
	v_lshlrev_b64 v[144:145], 1, v[144:145]
	v_cvt_pk_bf16_f32 v110, v110, v111
	v_cvt_pk_bf16_f32 v111, v112, v113
	v_cvt_pk_bf16_f32 v112, v106, v107
	v_or_b32_e32 v106, 16, v150
	v_mad_i64_i32 v[66:67], s[18:19], v66, s33, v[146:147]
	v_cvt_pk_bf16_f32 v46, v46, v47
	v_cvt_pk_bf16_f32 v47, v48, v49
	v_cvt_pk_bf16_f32 v48, v42, v43
	v_add_u32_e32 v42, 0x90, v150
	v_lshl_add_u64 v[148:149], v[148:149], 0, v[144:145]
	v_cvt_pk_bf16_f32 v113, v108, v109
	v_mad_i64_i32 v[106:107], s[18:19], v106, s33, v[146:147]
	v_cvt_pk_bf16_f32 v94, v94, v95
	v_cvt_pk_bf16_f32 v95, v96, v97
	v_cvt_pk_bf16_f32 v96, v90, v91
	v_or_b32_e32 v90, 32, v150
	v_lshl_add_u64 v[66:67], v[66:67], 0, v[144:145]
	v_cvt_pk_bf16_f32 v49, v44, v45
	v_mad_i64_i32 v[42:43], s[18:19], v42, s33, v[146:147]
	v_cvt_pk_bf16_f32 v30, v30, v31
	v_cvt_pk_bf16_f32 v31, v32, v33
	v_cvt_pk_bf16_f32 v32, v26, v27
	v_add_u32_e32 v26, 0xa0, v150
	global_store_dwordx4 v[148:149], v[110:113], off offset:256 sc1
	v_cvt_pk_bf16_f32 v97, v92, v93
	v_mad_i64_i32 v[90:91], s[18:19], v90, s33, v[146:147]
	v_lshl_add_u64 v[110:111], v[106:107], 0, v[144:145]
	v_cvt_pk_bf16_f32 v78, v78, v79
	v_cvt_pk_bf16_f32 v79, v80, v81
	v_cvt_pk_bf16_f32 v80, v74, v75
	v_or_b32_e32 v74, 48, v150
	global_store_dwordx4 v[66:67], v[46:49], off offset:256 sc1
	v_cvt_pk_bf16_f32 v33, v28, v29
	v_mad_i64_i32 v[26:27], s[18:19], v26, s33, v[146:147]
	v_lshl_add_u64 v[46:47], v[42:43], 0, v[144:145]
	v_cvt_pk_bf16_f32 v14, v14, v15
	v_cvt_pk_bf16_f32 v15, v16, v17
	v_cvt_pk_bf16_f32 v16, v10, v11
	v_add_u32_e32 v10, 0xb0, v150
	global_store_dwordx4 v[110:111], v[94:97], off offset:256 sc1
	v_cvt_pk_bf16_f32 v81, v76, v77
	v_mad_i64_i32 v[74:75], s[18:19], v74, s33, v[146:147]
	v_lshl_add_u64 v[94:95], v[90:91], 0, v[144:145]
	global_store_dwordx4 v[46:47], v[30:33], off offset:256 sc1
	v_cvt_pk_bf16_f32 v17, v12, v13
	v_mad_i64_i32 v[10:11], s[18:19], v10, s33, v[146:147]
	v_lshl_add_u64 v[30:31], v[26:27], 0, v[144:145]
	v_cvt_pk_bf16_f32 v126, v126, v127
	v_cvt_pk_bf16_f32 v127, v128, v129
	v_cvt_pk_bf16_f32 v128, v122, v123
	v_cvt_pk_bf16_f32 v129, v124, v125
	v_cvt_pk_bf16_f32 v106, v118, v119
	v_cvt_pk_bf16_f32 v107, v120, v121
	v_cvt_pk_bf16_f32 v108, v114, v115
	v_cvt_pk_bf16_f32 v109, v116, v117
	v_cvt_pk_bf16_f32 v90, v102, v103
	v_cvt_pk_bf16_f32 v91, v104, v105
	v_cvt_pk_bf16_f32 v92, v98, v99
	v_cvt_pk_bf16_f32 v93, v100, v101
	global_store_dwordx4 v[94:95], v[78:81], off offset:256 sc1
	v_cvt_pk_bf16_f32 v76, v82, v83
	v_cvt_pk_bf16_f32 v77, v84, v85
	v_lshl_add_u64 v[78:79], v[74:75], 0, v[144:145]
	v_cvt_pk_bf16_f32 v74, v86, v87
	v_cvt_pk_bf16_f32 v75, v88, v89
	v_cvt_pk_bf16_f32 v73, v68, v69
	v_cvt_pk_bf16_f32 v62, v62, v63
	v_cvt_pk_bf16_f32 v63, v64, v65
	v_cvt_pk_bf16_f32 v64, v58, v59
	v_cvt_pk_bf16_f32 v65, v60, v61
	v_cvt_pk_bf16_f32 v42, v54, v55
	v_cvt_pk_bf16_f32 v43, v56, v57
	v_cvt_pk_bf16_f32 v44, v50, v51
	v_cvt_pk_bf16_f32 v45, v52, v53
	v_cvt_pk_bf16_f32 v26, v38, v39
	v_cvt_pk_bf16_f32 v27, v40, v41
	v_cvt_pk_bf16_f32 v28, v34, v35
	v_cvt_pk_bf16_f32 v29, v36, v37
	global_store_dwordx4 v[30:31], v[14:17], off offset:256 sc1
	v_cvt_pk_bf16_f32 v12, v18, v19
	v_cvt_pk_bf16_f32 v13, v20, v21
	v_lshl_add_u64 v[14:15], v[10:11], 0, v[144:145]
	v_cvt_pk_bf16_f32 v10, v22, v23
	v_cvt_pk_bf16_f32 v11, v24, v25
	v_cvt_pk_bf16_f32 v6, v6, v7
	v_cvt_pk_bf16_f32 v7, v8, v9
	v_cvt_pk_bf16_f32 v8, v2, v3
	v_cvt_pk_bf16_f32 v9, v4, v5
	s_andn2_b64 vcc, exec, s[38:39]
	s_mov_b64 s[18:19], -1
	global_store_dwordx4 v[148:149], v[126:129], off sc1
	global_store_dwordx4 v[110:111], v[106:109], off sc1
	global_store_dwordx4 v[94:95], v[90:93], off sc1
	global_store_dwordx4 v[78:79], v[74:77], off sc1
	global_store_dwordx4 v[78:79], v[70:73], off offset:256 sc1
	global_store_dwordx4 v[66:67], v[62:65], off sc1
	global_store_dwordx4 v[46:47], v[42:45], off sc1
	global_store_dwordx4 v[30:31], v[26:29], off sc1
	global_store_dwordx4 v[14:15], v[10:13], off sc1
	global_store_dwordx4 v[14:15], v[6:9], off offset:256 sc1
	s_cbranch_vccnz .LBB0_209
	s_andn2_b64 vcc, exec, s[2:3]
	s_cbranch_vccnz .LBB0_208
	s_barrier
	s_branch .LBB0_208

.LBB0_687:
	v_mul_f32_e32 v122, 0xbfb8aa3b, v122
	v_exp_f32_e32 v122, v122
	v_mul_f32_e32 v127, 0xbfb8aa3b, v127
	v_exp_f32_e32 v127, v127
	v_mul_f32_e32 v123, 0xbfb8aa3b, v123
	v_add_f32_e32 v122, 1.0, v122
	v_exp_f32_e32 v123, v123
	v_rcp_f32_e32 v149, v122
	v_add_f32_e32 v122, 1.0, v127
	v_mul_f32_e32 v127, 0xbfb8aa3b, v128
	v_exp_f32_e32 v127, v127
	v_add_f32_e32 v123, 1.0, v123
	v_mul_f32_e32 v124, 0xbfb8aa3b, v124
	v_mul_f32_e32 v126, 0xbfb8aa3b, v126
	v_exp_f32_e32 v124, v124
	v_rcp_f32_e32 v128, v123
	v_add_f32_e32 v123, 1.0, v127
	v_mul_f32_e32 v127, 0xbfb8aa3b, v129
	v_mul_f32_e32 v125, 0xbfb8aa3b, v125
	v_exp_f32_e32 v126, v126
	v_exp_f32_e32 v127, v127
	v_exp_f32_e32 v125, v125
	v_add_f32_e32 v124, 1.0, v124
	v_add_f32_e32 v126, 1.0, v126
	v_rcp_f32_e32 v129, v124
	v_add_f32_e32 v124, 1.0, v127
	v_add_f32_e32 v125, 1.0, v125
	v_mul_f32_e32 v114, 0xbfb8aa3b, v114
	v_rcp_f32_e32 v126, v126
	v_rcp_f32_e32 v122, v122
	v_rcp_f32_e32 v123, v123
	v_rcp_f32_e32 v124, v124
	v_rcp_f32_e32 v125, v125
	v_exp_f32_e32 v114, v114
	v_mul_f32_e32 v119, 0xbfb8aa3b, v119
	v_lshl_or_b32 v140, s19, 8, v146
	v_exp_f32_e32 v119, v119
	v_lshl_add_u32 v148, s18, 8, v144
	v_ashrrev_i32_e32 v141, 31, v140
	v_mov_b64_e32 v[142:143], s[4:5]
	v_mad_i64_i32 v[150:151], s[18:19], v148, s81, v[142:143]
	v_lshlrev_b64 v[140:141], 1, v[140:141]
	v_lshl_add_u64 v[150:151], v[150:151], 0, v[140:141]
	v_cvt_pk_bf16_f32 v122, v126, v122
	v_cvt_pk_bf16_f32 v123, v123, v124
	v_cvt_pk_bf16_f32 v124, v149, v128
	v_cvt_pk_bf16_f32 v125, v129, v125
	v_add_f32_e32 v114, 1.0, v114
	v_mul_f32_e32 v115, 0xbfb8aa3b, v115
	global_store_dwordx4 v[150:151], v[122:125], off sc1
	v_exp_f32_e32 v115, v115
	v_mul_f32_e32 v116, 0xbfb8aa3b, v116
	v_rcp_f32_e32 v122, v114
	v_add_f32_e32 v114, 1.0, v119
	v_mul_f32_e32 v119, 0xbfb8aa3b, v120
	v_exp_f32_e32 v119, v119
	v_add_f32_e32 v115, 1.0, v115
	v_mul_f32_e32 v118, 0xbfb8aa3b, v118
	v_exp_f32_e32 v116, v116
	v_rcp_f32_e32 v120, v115
	v_add_f32_e32 v115, 1.0, v119
	v_mul_f32_e32 v119, 0xbfb8aa3b, v121
	v_mul_f32_e32 v117, 0xbfb8aa3b, v117
	v_exp_f32_e32 v118, v118
	v_exp_f32_e32 v119, v119
	v_exp_f32_e32 v117, v117
	v_add_f32_e32 v116, 1.0, v116
	v_add_f32_e32 v118, 1.0, v118
	v_rcp_f32_e32 v121, v116
	v_add_f32_e32 v116, 1.0, v119
	v_add_f32_e32 v117, 1.0, v117
	v_mul_f32_e32 v106, 0xbfb8aa3b, v106
	v_rcp_f32_e32 v118, v118
	v_rcp_f32_e32 v114, v114
	v_rcp_f32_e32 v115, v115
	v_rcp_f32_e32 v116, v116
	v_rcp_f32_e32 v117, v117
	v_exp_f32_e32 v106, v106
	v_mul_f32_e32 v111, 0xbfb8aa3b, v111
	v_exp_f32_e32 v111, v111
	v_cvt_pk_bf16_f32 v114, v118, v114
	v_cvt_pk_bf16_f32 v115, v115, v116
	v_cvt_pk_bf16_f32 v116, v122, v120
	v_cvt_pk_bf16_f32 v117, v121, v117
	v_add_f32_e32 v106, 1.0, v106
	v_mul_f32_e32 v107, 0xbfb8aa3b, v107
	global_store_dwordx4 v[150:151], v[114:117], off offset:256 sc1
	v_exp_f32_e32 v107, v107
	v_mul_f32_e32 v108, 0xbfb8aa3b, v108
	v_rcp_f32_e32 v116, v106
	v_add_f32_e32 v106, 1.0, v111
	v_mul_f32_e32 v111, 0xbfb8aa3b, v112
	v_exp_f32_e32 v111, v111
	v_add_f32_e32 v107, 1.0, v107
	v_mul_f32_e32 v110, 0xbfb8aa3b, v110
	v_exp_f32_e32 v108, v108
	v_rcp_f32_e32 v112, v107
	v_add_f32_e32 v107, 1.0, v111
	v_mul_f32_e32 v111, 0xbfb8aa3b, v113
	v_mul_f32_e32 v109, 0xbfb8aa3b, v109
	v_exp_f32_e32 v110, v110
	v_exp_f32_e32 v111, v111
	v_exp_f32_e32 v109, v109
	v_add_f32_e32 v108, 1.0, v108
	v_add_f32_e32 v110, 1.0, v110
	v_rcp_f32_e32 v113, v108
	v_add_f32_e32 v108, 1.0, v111
	v_add_f32_e32 v109, 1.0, v109
	v_mul_f32_e32 v98, 0xbfb8aa3b, v98
	v_rcp_f32_e32 v110, v110
	v_rcp_f32_e32 v106, v106
	v_rcp_f32_e32 v107, v107
	v_rcp_f32_e32 v108, v108
	v_rcp_f32_e32 v109, v109
	v_exp_f32_e32 v98, v98
	v_mul_f32_e32 v103, 0xbfb8aa3b, v103
	v_exp_f32_e32 v103, v103
	v_or_b32_e32 v114, 16, v148
	v_mad_i64_i32 v[114:115], s[18:19], v114, s81, v[142:143]
	v_lshl_add_u64 v[114:115], v[114:115], 0, v[140:141]
	v_cvt_pk_bf16_f32 v106, v110, v106
	v_cvt_pk_bf16_f32 v107, v107, v108
	v_cvt_pk_bf16_f32 v108, v116, v112
	v_cvt_pk_bf16_f32 v109, v113, v109
	v_add_f32_e32 v98, 1.0, v98
	v_mul_f32_e32 v99, 0xbfb8aa3b, v99
	global_store_dwordx4 v[114:115], v[106:109], off sc1
	v_exp_f32_e32 v99, v99
	v_mul_f32_e32 v100, 0xbfb8aa3b, v100
	v_rcp_f32_e32 v106, v98
	v_add_f32_e32 v98, 1.0, v103
	v_mul_f32_e32 v103, 0xbfb8aa3b, v104
	v_exp_f32_e32 v103, v103
	v_add_f32_e32 v99, 1.0, v99
	v_mul_f32_e32 v102, 0xbfb8aa3b, v102
	v_exp_f32_e32 v100, v100
	v_rcp_f32_e32 v104, v99
	v_add_f32_e32 v99, 1.0, v103
	v_mul_f32_e32 v103, 0xbfb8aa3b, v105
	v_mul_f32_e32 v101, 0xbfb8aa3b, v101
	v_exp_f32_e32 v102, v102
	v_exp_f32_e32 v103, v103
	v_exp_f32_e32 v101, v101
	v_add_f32_e32 v100, 1.0, v100
	v_add_f32_e32 v102, 1.0, v102
	v_rcp_f32_e32 v105, v100
	v_add_f32_e32 v100, 1.0, v103
	v_add_f32_e32 v101, 1.0, v101
	v_mul_f32_e32 v90, 0xbfb8aa3b, v90
	v_rcp_f32_e32 v102, v102
	v_rcp_f32_e32 v98, v98
	v_rcp_f32_e32 v99, v99
	v_rcp_f32_e32 v100, v100
	v_rcp_f32_e32 v101, v101
	v_exp_f32_e32 v90, v90
	v_mul_f32_e32 v95, 0xbfb8aa3b, v95
	v_exp_f32_e32 v95, v95
	v_cvt_pk_bf16_f32 v98, v102, v98
	v_cvt_pk_bf16_f32 v99, v99, v100
	v_cvt_pk_bf16_f32 v100, v106, v104
	v_cvt_pk_bf16_f32 v101, v105, v101
	v_add_f32_e32 v90, 1.0, v90
	v_mul_f32_e32 v91, 0xbfb8aa3b, v91
	global_store_dwordx4 v[114:115], v[98:101], off offset:256 sc1
	v_exp_f32_e32 v91, v91
	v_mul_f32_e32 v92, 0xbfb8aa3b, v92
	v_rcp_f32_e32 v100, v90
	v_add_f32_e32 v90, 1.0, v95
	v_mul_f32_e32 v95, 0xbfb8aa3b, v96
	v_exp_f32_e32 v95, v95
	v_add_f32_e32 v91, 1.0, v91
	v_mul_f32_e32 v94, 0xbfb8aa3b, v94
	v_exp_f32_e32 v92, v92
	v_rcp_f32_e32 v96, v91
	v_add_f32_e32 v91, 1.0, v95
	v_mul_f32_e32 v95, 0xbfb8aa3b, v97
	v_mul_f32_e32 v93, 0xbfb8aa3b, v93
	v_exp_f32_e32 v94, v94
	v_exp_f32_e32 v95, v95
	v_exp_f32_e32 v93, v93
	v_add_f32_e32 v92, 1.0, v92
	v_add_f32_e32 v94, 1.0, v94
	v_rcp_f32_e32 v97, v92
	v_add_f32_e32 v92, 1.0, v95
	v_add_f32_e32 v93, 1.0, v93
	v_mul_f32_e32 v82, 0xbfb8aa3b, v82
	v_rcp_f32_e32 v94, v94
	v_rcp_f32_e32 v90, v90
	v_rcp_f32_e32 v91, v91
	v_rcp_f32_e32 v92, v92
	v_rcp_f32_e32 v93, v93
	v_exp_f32_e32 v82, v82
	v_mul_f32_e32 v87, 0xbfb8aa3b, v87
	v_exp_f32_e32 v87, v87
	v_or_b32_e32 v98, 32, v148
	v_mad_i64_i32 v[98:99], s[18:19], v98, s81, v[142:143]
	v_lshl_add_u64 v[98:99], v[98:99], 0, v[140:141]
	v_cvt_pk_bf16_f32 v90, v94, v90
	v_cvt_pk_bf16_f32 v91, v91, v92
	v_cvt_pk_bf16_f32 v92, v100, v96
	v_cvt_pk_bf16_f32 v93, v97, v93
	v_add_f32_e32 v82, 1.0, v82
	v_mul_f32_e32 v83, 0xbfb8aa3b, v83
	global_store_dwordx4 v[98:99], v[90:93], off sc1
	v_exp_f32_e32 v83, v83
	v_mul_f32_e32 v84, 0xbfb8aa3b, v84
	v_rcp_f32_e32 v90, v82
	v_add_f32_e32 v82, 1.0, v87
	v_mul_f32_e32 v87, 0xbfb8aa3b, v88
	v_exp_f32_e32 v87, v87
	v_add_f32_e32 v83, 1.0, v83
	v_mul_f32_e32 v86, 0xbfb8aa3b, v86
	v_exp_f32_e32 v84, v84
	v_rcp_f32_e32 v88, v83
	v_add_f32_e32 v83, 1.0, v87
	v_mul_f32_e32 v87, 0xbfb8aa3b, v89
	v_mul_f32_e32 v85, 0xbfb8aa3b, v85
	v_exp_f32_e32 v86, v86
	v_exp_f32_e32 v87, v87
	v_exp_f32_e32 v85, v85
	v_add_f32_e32 v84, 1.0, v84
	v_add_f32_e32 v86, 1.0, v86
	v_rcp_f32_e32 v89, v84
	v_add_f32_e32 v84, 1.0, v87
	v_add_f32_e32 v85, 1.0, v85
	v_mul_f32_e32 v74, 0xbfb8aa3b, v74
	v_rcp_f32_e32 v86, v86
	v_rcp_f32_e32 v82, v82
	v_rcp_f32_e32 v83, v83
	v_rcp_f32_e32 v84, v84
	v_rcp_f32_e32 v85, v85
	v_exp_f32_e32 v74, v74
	v_mul_f32_e32 v79, 0xbfb8aa3b, v79
	v_exp_f32_e32 v79, v79
	v_cvt_pk_bf16_f32 v82, v86, v82
	v_cvt_pk_bf16_f32 v83, v83, v84
	v_cvt_pk_bf16_f32 v84, v90, v88
	v_cvt_pk_bf16_f32 v85, v89, v85
	v_add_f32_e32 v74, 1.0, v74
	v_mul_f32_e32 v75, 0xbfb8aa3b, v75
	global_store_dwordx4 v[98:99], v[82:85], off offset:256 sc1
	v_exp_f32_e32 v75, v75
	v_mul_f32_e32 v76, 0xbfb8aa3b, v76
	v_rcp_f32_e32 v84, v74
	v_add_f32_e32 v74, 1.0, v79
	v_mul_f32_e32 v79, 0xbfb8aa3b, v80
	v_exp_f32_e32 v79, v79
	v_add_f32_e32 v75, 1.0, v75
	v_mul_f32_e32 v78, 0xbfb8aa3b, v78
	v_exp_f32_e32 v76, v76
	v_rcp_f32_e32 v80, v75
	v_add_f32_e32 v75, 1.0, v79
	v_mul_f32_e32 v79, 0xbfb8aa3b, v81
	v_mul_f32_e32 v77, 0xbfb8aa3b, v77
	v_exp_f32_e32 v78, v78
	v_exp_f32_e32 v79, v79
	v_exp_f32_e32 v77, v77
	v_add_f32_e32 v76, 1.0, v76
	v_add_f32_e32 v78, 1.0, v78
	v_rcp_f32_e32 v81, v76
	v_add_f32_e32 v76, 1.0, v79
	v_add_f32_e32 v77, 1.0, v77
	v_mul_f32_e32 v66, 0xbfb8aa3b, v66
	v_rcp_f32_e32 v78, v78
	v_rcp_f32_e32 v74, v74
	v_rcp_f32_e32 v75, v75
	v_rcp_f32_e32 v76, v76
	v_rcp_f32_e32 v77, v77
	v_exp_f32_e32 v66, v66
	v_mul_f32_e32 v71, 0xbfb8aa3b, v71
	v_exp_f32_e32 v71, v71
	v_or_b32_e32 v82, 48, v148
	v_mad_i64_i32 v[82:83], s[18:19], v82, s81, v[142:143]
	v_lshl_add_u64 v[82:83], v[82:83], 0, v[140:141]
	v_cvt_pk_bf16_f32 v74, v78, v74
	v_cvt_pk_bf16_f32 v75, v75, v76
	v_cvt_pk_bf16_f32 v76, v84, v80
	v_cvt_pk_bf16_f32 v77, v81, v77
	v_add_f32_e32 v66, 1.0, v66
	v_mul_f32_e32 v67, 0xbfb8aa3b, v67
	global_store_dwordx4 v[82:83], v[74:77], off sc1
	v_exp_f32_e32 v67, v67
	v_mul_f32_e32 v68, 0xbfb8aa3b, v68
	v_rcp_f32_e32 v74, v66
	v_add_f32_e32 v66, 1.0, v71
	v_mul_f32_e32 v71, 0xbfb8aa3b, v72
	v_exp_f32_e32 v71, v71
	v_add_f32_e32 v67, 1.0, v67
	v_mul_f32_e32 v70, 0xbfb8aa3b, v70
	v_exp_f32_e32 v68, v68
	v_rcp_f32_e32 v72, v67
	v_add_f32_e32 v67, 1.0, v71
	v_mul_f32_e32 v71, 0xbfb8aa3b, v73
	v_mul_f32_e32 v69, 0xbfb8aa3b, v69
	v_exp_f32_e32 v70, v70
	v_exp_f32_e32 v71, v71
	v_exp_f32_e32 v69, v69
	v_add_f32_e32 v68, 1.0, v68
	v_add_f32_e32 v70, 1.0, v70
	v_rcp_f32_e32 v73, v68
	v_add_f32_e32 v68, 1.0, v71
	v_add_f32_e32 v69, 1.0, v69
	v_mul_f32_e32 v58, 0xbfb8aa3b, v58
	v_rcp_f32_e32 v70, v70
	v_rcp_f32_e32 v66, v66
	v_rcp_f32_e32 v67, v67
	v_rcp_f32_e32 v68, v68
	v_rcp_f32_e32 v69, v69
	v_exp_f32_e32 v58, v58
	v_mul_f32_e32 v63, 0xbfb8aa3b, v63
	v_exp_f32_e32 v63, v63
	v_cvt_pk_bf16_f32 v66, v70, v66
	v_cvt_pk_bf16_f32 v67, v67, v68
	v_cvt_pk_bf16_f32 v68, v74, v72
	v_cvt_pk_bf16_f32 v69, v73, v69
	v_add_f32_e32 v58, 1.0, v58
	v_mul_f32_e32 v59, 0xbfb8aa3b, v59
	global_store_dwordx4 v[82:83], v[66:69], off offset:256 sc1
	v_exp_f32_e32 v59, v59
	v_mul_f32_e32 v60, 0xbfb8aa3b, v60
	v_rcp_f32_e32 v68, v58
	v_add_f32_e32 v58, 1.0, v63
	v_mul_f32_e32 v63, 0xbfb8aa3b, v64
	v_exp_f32_e32 v63, v63
	v_add_f32_e32 v59, 1.0, v59
	v_mul_f32_e32 v62, 0xbfb8aa3b, v62
	v_exp_f32_e32 v60, v60
	v_rcp_f32_e32 v64, v59
	v_add_f32_e32 v59, 1.0, v63
	v_mul_f32_e32 v63, 0xbfb8aa3b, v65
	v_mul_f32_e32 v61, 0xbfb8aa3b, v61
	v_exp_f32_e32 v62, v62
	v_exp_f32_e32 v63, v63
	v_exp_f32_e32 v61, v61
	v_add_f32_e32 v60, 1.0, v60
	v_add_f32_e32 v62, 1.0, v62
	v_rcp_f32_e32 v65, v60
	v_add_f32_e32 v60, 1.0, v63
	v_add_f32_e32 v61, 1.0, v61
	v_mul_f32_e32 v50, 0xbfb8aa3b, v50
	v_rcp_f32_e32 v62, v62
	v_rcp_f32_e32 v58, v58
	v_rcp_f32_e32 v59, v59
	v_rcp_f32_e32 v60, v60
	v_rcp_f32_e32 v61, v61
	v_exp_f32_e32 v50, v50
	v_mul_f32_e32 v55, 0xbfb8aa3b, v55
	v_exp_f32_e32 v55, v55
	v_add_u32_e32 v66, 0x80, v148
	v_mad_i64_i32 v[66:67], s[18:19], v66, s81, v[142:143]
	v_lshl_add_u64 v[66:67], v[66:67], 0, v[140:141]
	v_cvt_pk_bf16_f32 v58, v62, v58
	v_cvt_pk_bf16_f32 v59, v59, v60
	v_cvt_pk_bf16_f32 v60, v68, v64
	v_cvt_pk_bf16_f32 v61, v65, v61
	v_add_f32_e32 v50, 1.0, v50
	v_mul_f32_e32 v51, 0xbfb8aa3b, v51
	global_store_dwordx4 v[66:67], v[58:61], off sc1
	v_exp_f32_e32 v51, v51
	v_mul_f32_e32 v52, 0xbfb8aa3b, v52
	v_rcp_f32_e32 v58, v50
	v_add_f32_e32 v50, 1.0, v55
	v_mul_f32_e32 v55, 0xbfb8aa3b, v56
	v_exp_f32_e32 v55, v55
	v_add_f32_e32 v51, 1.0, v51
	v_mul_f32_e32 v54, 0xbfb8aa3b, v54
	v_exp_f32_e32 v52, v52
	v_rcp_f32_e32 v56, v51
	v_add_f32_e32 v51, 1.0, v55
	v_mul_f32_e32 v55, 0xbfb8aa3b, v57
	v_mul_f32_e32 v53, 0xbfb8aa3b, v53
	v_exp_f32_e32 v54, v54
	v_exp_f32_e32 v55, v55
	v_exp_f32_e32 v53, v53
	v_add_f32_e32 v52, 1.0, v52
	v_add_f32_e32 v54, 1.0, v54
	v_rcp_f32_e32 v57, v52
	v_add_f32_e32 v52, 1.0, v55
	v_add_f32_e32 v53, 1.0, v53
	v_mul_f32_e32 v42, 0xbfb8aa3b, v42
	v_rcp_f32_e32 v54, v54
	v_rcp_f32_e32 v50, v50
	v_rcp_f32_e32 v51, v51
	v_rcp_f32_e32 v52, v52
	v_rcp_f32_e32 v53, v53
	v_exp_f32_e32 v42, v42
	v_mul_f32_e32 v47, 0xbfb8aa3b, v47
	v_exp_f32_e32 v47, v47
	v_cvt_pk_bf16_f32 v50, v54, v50
	v_cvt_pk_bf16_f32 v51, v51, v52
	v_cvt_pk_bf16_f32 v52, v58, v56
	v_cvt_pk_bf16_f32 v53, v57, v53
	v_add_f32_e32 v42, 1.0, v42
	v_mul_f32_e32 v43, 0xbfb8aa3b, v43
	global_store_dwordx4 v[66:67], v[50:53], off offset:256 sc1
	v_exp_f32_e32 v43, v43
	v_mul_f32_e32 v44, 0xbfb8aa3b, v44
	v_rcp_f32_e32 v52, v42
	v_add_f32_e32 v42, 1.0, v47
	v_mul_f32_e32 v47, 0xbfb8aa3b, v48
	v_exp_f32_e32 v47, v47
	v_add_f32_e32 v43, 1.0, v43
	v_mul_f32_e32 v46, 0xbfb8aa3b, v46
	v_exp_f32_e32 v44, v44
	v_rcp_f32_e32 v48, v43
	v_add_f32_e32 v43, 1.0, v47
	v_mul_f32_e32 v47, 0xbfb8aa3b, v49
	v_mul_f32_e32 v45, 0xbfb8aa3b, v45
	v_exp_f32_e32 v46, v46
	v_exp_f32_e32 v47, v47
	v_exp_f32_e32 v45, v45
	v_add_f32_e32 v44, 1.0, v44
	v_add_f32_e32 v46, 1.0, v46
	v_rcp_f32_e32 v49, v44
	v_add_f32_e32 v44, 1.0, v47
	v_add_f32_e32 v45, 1.0, v45
	v_mul_f32_e32 v34, 0xbfb8aa3b, v34
	v_rcp_f32_e32 v46, v46
	v_rcp_f32_e32 v42, v42
	v_rcp_f32_e32 v43, v43
	v_rcp_f32_e32 v44, v44
	v_rcp_f32_e32 v45, v45
	v_exp_f32_e32 v34, v34
	v_mul_f32_e32 v39, 0xbfb8aa3b, v39
	v_exp_f32_e32 v39, v39
	v_add_u32_e32 v50, 0x90, v148
	v_mad_i64_i32 v[50:51], s[18:19], v50, s81, v[142:143]
	v_lshl_add_u64 v[50:51], v[50:51], 0, v[140:141]
	v_cvt_pk_bf16_f32 v42, v46, v42
	v_cvt_pk_bf16_f32 v43, v43, v44
	v_cvt_pk_bf16_f32 v44, v52, v48
	v_cvt_pk_bf16_f32 v45, v49, v45
	v_add_f32_e32 v34, 1.0, v34
	v_mul_f32_e32 v35, 0xbfb8aa3b, v35
	global_store_dwordx4 v[50:51], v[42:45], off sc1
	v_exp_f32_e32 v35, v35
	v_mul_f32_e32 v36, 0xbfb8aa3b, v36
	v_rcp_f32_e32 v42, v34
	v_add_f32_e32 v34, 1.0, v39
	v_mul_f32_e32 v39, 0xbfb8aa3b, v40
	v_exp_f32_e32 v39, v39
	v_add_f32_e32 v35, 1.0, v35
	v_mul_f32_e32 v38, 0xbfb8aa3b, v38
	v_exp_f32_e32 v36, v36
	v_rcp_f32_e32 v40, v35
	v_add_f32_e32 v35, 1.0, v39
	v_mul_f32_e32 v39, 0xbfb8aa3b, v41
	v_mul_f32_e32 v37, 0xbfb8aa3b, v37
	v_exp_f32_e32 v38, v38
	v_exp_f32_e32 v39, v39
	v_exp_f32_e32 v37, v37
	v_add_f32_e32 v36, 1.0, v36
	v_add_f32_e32 v38, 1.0, v38
	v_rcp_f32_e32 v41, v36
	v_add_f32_e32 v36, 1.0, v39
	v_add_f32_e32 v37, 1.0, v37
	v_mul_f32_e32 v26, 0xbfb8aa3b, v26
	v_rcp_f32_e32 v38, v38
	v_rcp_f32_e32 v34, v34
	v_rcp_f32_e32 v35, v35
	v_rcp_f32_e32 v36, v36
	v_rcp_f32_e32 v37, v37
	v_exp_f32_e32 v26, v26
	v_mul_f32_e32 v31, 0xbfb8aa3b, v31
	v_exp_f32_e32 v31, v31
	v_cvt_pk_bf16_f32 v34, v38, v34
	v_cvt_pk_bf16_f32 v35, v35, v36
	v_cvt_pk_bf16_f32 v36, v42, v40
	v_cvt_pk_bf16_f32 v37, v41, v37
	v_add_f32_e32 v26, 1.0, v26
	v_mul_f32_e32 v27, 0xbfb8aa3b, v27
	global_store_dwordx4 v[50:51], v[34:37], off offset:256 sc1
	v_exp_f32_e32 v27, v27
	v_mul_f32_e32 v28, 0xbfb8aa3b, v28
	v_rcp_f32_e32 v36, v26
	v_add_f32_e32 v26, 1.0, v31
	v_mul_f32_e32 v31, 0xbfb8aa3b, v32
	v_exp_f32_e32 v31, v31
	v_add_f32_e32 v27, 1.0, v27
	v_mul_f32_e32 v30, 0xbfb8aa3b, v30
	v_exp_f32_e32 v28, v28
	v_rcp_f32_e32 v32, v27
	v_add_f32_e32 v27, 1.0, v31
	v_mul_f32_e32 v31, 0xbfb8aa3b, v33
	v_mul_f32_e32 v29, 0xbfb8aa3b, v29
	v_exp_f32_e32 v30, v30
	v_exp_f32_e32 v31, v31
	v_exp_f32_e32 v29, v29
	v_add_f32_e32 v28, 1.0, v28
	v_add_f32_e32 v30, 1.0, v30
	v_rcp_f32_e32 v33, v28
	v_add_f32_e32 v28, 1.0, v31
	v_add_f32_e32 v29, 1.0, v29
	v_mul_f32_e32 v18, 0xbfb8aa3b, v18
	v_rcp_f32_e32 v30, v30
	v_rcp_f32_e32 v26, v26
	v_rcp_f32_e32 v27, v27
	v_rcp_f32_e32 v28, v28
	v_rcp_f32_e32 v29, v29
	v_exp_f32_e32 v18, v18
	v_mul_f32_e32 v23, 0xbfb8aa3b, v23
	v_exp_f32_e32 v23, v23
	v_add_u32_e32 v34, 0xa0, v148
	v_mad_i64_i32 v[34:35], s[18:19], v34, s81, v[142:143]
	v_lshl_add_u64 v[34:35], v[34:35], 0, v[140:141]
	v_cvt_pk_bf16_f32 v26, v30, v26
	v_cvt_pk_bf16_f32 v27, v27, v28
	v_cvt_pk_bf16_f32 v28, v36, v32
	v_cvt_pk_bf16_f32 v29, v33, v29
	v_add_f32_e32 v18, 1.0, v18
	v_mul_f32_e32 v19, 0xbfb8aa3b, v19
	global_store_dwordx4 v[34:35], v[26:29], off sc1
	v_exp_f32_e32 v19, v19
	v_mul_f32_e32 v20, 0xbfb8aa3b, v20
	v_rcp_f32_e32 v26, v18
	v_add_f32_e32 v18, 1.0, v23
	v_mul_f32_e32 v23, 0xbfb8aa3b, v24
	v_exp_f32_e32 v23, v23
	v_add_f32_e32 v19, 1.0, v19
	v_mul_f32_e32 v22, 0xbfb8aa3b, v22
	v_exp_f32_e32 v20, v20
	v_rcp_f32_e32 v24, v19
	v_add_f32_e32 v19, 1.0, v23
	v_mul_f32_e32 v23, 0xbfb8aa3b, v25
	v_mul_f32_e32 v21, 0xbfb8aa3b, v21
	v_exp_f32_e32 v22, v22
	v_exp_f32_e32 v23, v23
	v_exp_f32_e32 v21, v21
	v_add_f32_e32 v20, 1.0, v20
	v_add_f32_e32 v22, 1.0, v22
	v_rcp_f32_e32 v25, v20
	v_add_f32_e32 v20, 1.0, v23
	v_add_f32_e32 v21, 1.0, v21
	v_mul_f32_e32 v10, 0xbfb8aa3b, v10
	v_rcp_f32_e32 v22, v22
	v_rcp_f32_e32 v18, v18
	v_rcp_f32_e32 v19, v19
	v_rcp_f32_e32 v20, v20
	v_rcp_f32_e32 v21, v21
	v_exp_f32_e32 v10, v10
	v_mul_f32_e32 v15, 0xbfb8aa3b, v15
	v_exp_f32_e32 v15, v15
	v_cvt_pk_bf16_f32 v18, v22, v18
	v_cvt_pk_bf16_f32 v19, v19, v20
	v_cvt_pk_bf16_f32 v20, v26, v24
	v_cvt_pk_bf16_f32 v21, v25, v21
	v_add_f32_e32 v10, 1.0, v10
	v_mul_f32_e32 v11, 0xbfb8aa3b, v11
	global_store_dwordx4 v[34:35], v[18:21], off offset:256 sc1
	v_exp_f32_e32 v11, v11
	v_mul_f32_e32 v12, 0xbfb8aa3b, v12
	v_rcp_f32_e32 v20, v10
	v_add_f32_e32 v10, 1.0, v15
	v_mul_f32_e32 v15, 0xbfb8aa3b, v16
	v_exp_f32_e32 v15, v15
	v_add_f32_e32 v11, 1.0, v11
	v_mul_f32_e32 v14, 0xbfb8aa3b, v14
	v_exp_f32_e32 v12, v12
	v_rcp_f32_e32 v16, v11
	v_add_f32_e32 v11, 1.0, v15
	v_mul_f32_e32 v15, 0xbfb8aa3b, v17
	v_mul_f32_e32 v13, 0xbfb8aa3b, v13
	v_exp_f32_e32 v14, v14
	v_exp_f32_e32 v15, v15
	v_exp_f32_e32 v13, v13
	v_add_f32_e32 v12, 1.0, v12
	v_add_f32_e32 v14, 1.0, v14
	v_rcp_f32_e32 v17, v12
	v_add_f32_e32 v12, 1.0, v15
	v_add_f32_e32 v13, 1.0, v13
	v_mul_f32_e32 v2, 0xbfb8aa3b, v2
	v_rcp_f32_e32 v14, v14
	v_rcp_f32_e32 v10, v10
	v_rcp_f32_e32 v11, v11
	v_rcp_f32_e32 v12, v12
	v_rcp_f32_e32 v13, v13
	v_exp_f32_e32 v2, v2
	v_mul_f32_e32 v7, 0xbfb8aa3b, v7
	v_exp_f32_e32 v7, v7
	v_add_u32_e32 v18, 0xb0, v148
	v_mad_i64_i32 v[18:19], s[18:19], v18, s81, v[142:143]
	v_lshl_add_u64 v[18:19], v[18:19], 0, v[140:141]
	v_cvt_pk_bf16_f32 v10, v14, v10
	v_cvt_pk_bf16_f32 v11, v11, v12
	v_cvt_pk_bf16_f32 v12, v20, v16
	v_cvt_pk_bf16_f32 v13, v17, v13
	v_add_f32_e32 v2, 1.0, v2
	v_mul_f32_e32 v3, 0xbfb8aa3b, v3
	global_store_dwordx4 v[18:19], v[10:13], off sc1
	v_exp_f32_e32 v3, v3
	v_mul_f32_e32 v4, 0xbfb8aa3b, v4
	v_rcp_f32_e32 v10, v2
	v_add_f32_e32 v2, 1.0, v7
	v_mul_f32_e32 v7, 0xbfb8aa3b, v8
	v_exp_f32_e32 v7, v7
	v_add_f32_e32 v3, 1.0, v3
	v_mul_f32_e32 v6, 0xbfb8aa3b, v6
	v_exp_f32_e32 v4, v4
	v_rcp_f32_e32 v8, v3
	v_add_f32_e32 v3, 1.0, v7
	v_mul_f32_e32 v7, 0xbfb8aa3b, v9
	v_mul_f32_e32 v5, 0xbfb8aa3b, v5
	v_exp_f32_e32 v6, v6
	v_exp_f32_e32 v7, v7
	v_exp_f32_e32 v5, v5
	v_add_f32_e32 v4, 1.0, v4
	v_add_f32_e32 v6, 1.0, v6
	v_rcp_f32_e32 v9, v4
	v_add_f32_e32 v4, 1.0, v7
	v_add_f32_e32 v5, 1.0, v5
	v_rcp_f32_e32 v6, v6
	v_rcp_f32_e32 v2, v2
	v_rcp_f32_e32 v3, v3
	v_rcp_f32_e32 v4, v4
	v_rcp_f32_e32 v5, v5
	v_cvt_pk_bf16_f32 v2, v6, v2
	s_andn2_b64 vcc, exec, s[40:41]
	v_cvt_pk_bf16_f32 v3, v3, v4
	v_cvt_pk_bf16_f32 v4, v10, v8
	v_cvt_pk_bf16_f32 v5, v9, v5
	s_mov_b64 s[18:19], -1
	global_store_dwordx4 v[18:19], v[2:5], off offset:256 sc1
	s_cbranch_vccnz .LBB0_679
	s_andn2_b64 vcc, exec, s[2:3]
	s_cbranch_vccnz .LBB0_678
	s_barrier
	s_branch .LBB0_678

.LBB0_1030:
	s_lshl_b32 s11, s14, 8
	s_add_i32 s11, s11, s55
	v_or_b32_e32 v148, s11, v144
	v_lshl_or_b32 v140, s18, 8, v146
	v_mov_b64_e32 v[142:143], s[4:5]
	s_movk_i32 s26, 0x2c00
	v_ashrrev_i32_e32 v141, 31, v140
	v_mad_i64_i32 v[142:143], s[14:15], v148, s26, v[142:143]
	s_ashr_i32 s11, s11, 4
	v_lshl_add_u64 v[142:143], v[140:141], 1, v[142:143]
	v_cvt_pk_bf16_f32 v126, v126, v127
	v_cvt_pk_bf16_f32 v127, v128, v129
	v_cvt_pk_bf16_f32 v128, v122, v123
	v_cvt_pk_bf16_f32 v129, v124, v125
	s_mul_hi_i32 s13, s11, 0x2c00
	s_mul_i32 s18, s11, 0x2c00
	global_store_dwordx4 v[142:143], v[126:129], off sc1
	s_and_saveexec_b64 s[14:15], s[42:43]
	s_cbranch_execz .LBB0_1032
	s_add_u32 s24, s6, s18
	s_addc_u32 s25, s7, s13
	v_lshl_add_u64 v[122:123], v[140:141], 1, s[24:25]
	global_store_dwordx4 v[122:123], v[126:129], off sc1
.LBB0_1032:
	s_or_b64 exec, exec, s[14:15]
	v_cvt_pk_bf16_f32 v118, v118, v119
	v_cvt_pk_bf16_f32 v119, v120, v121
	v_cvt_pk_bf16_f32 v120, v110, v111
	v_cvt_pk_bf16_f32 v121, v112, v113
	global_store_dwordx4 v[142:143], v[118:121], off offset:256 sc1
	s_and_saveexec_b64 s[14:15], s[42:43]
	s_cbranch_execz .LBB0_1034
	s_add_u32 s24, s6, s18
	s_addc_u32 s25, s7, s13
	v_lshl_add_u64 v[110:111], v[140:141], 1, s[24:25]
	global_store_dwordx4 v[110:111], v[118:121], off offset:256 sc1
.LBB0_1034:
	s_or_b64 exec, exec, s[14:15]
	v_or_b32_e32 v112, 16, v148
	v_mov_b64_e32 v[110:111], s[4:5]
	v_mad_i64_i32 v[110:111], s[14:15], v112, s26, v[110:111]
	s_or_b32 s13, s11, 1
	v_lshl_add_u64 v[118:119], v[140:141], 1, v[110:111]
	v_cvt_pk_bf16_f32 v110, v114, v115
	v_cvt_pk_bf16_f32 v111, v116, v117
	v_cvt_pk_bf16_f32 v112, v106, v107
	v_cvt_pk_bf16_f32 v113, v108, v109
	s_mul_hi_i32 s11, s13, 0x2c00
	s_mulk_i32 s13, 0x2c00
	global_store_dwordx4 v[118:119], v[110:113], off sc1
	s_and_saveexec_b64 s[14:15], s[40:41]
	s_cbranch_execz .LBB0_1036
	s_add_u32 s24, s6, s13
	s_addc_u32 s25, s7, s11
	v_lshl_add_u64 v[106:107], v[140:141], 1, s[24:25]
	global_store_dwordx4 v[106:107], v[110:113], off sc1
.LBB0_1036:
	s_or_b64 exec, exec, s[14:15]
	v_cvt_pk_bf16_f32 v102, v102, v103
	v_cvt_pk_bf16_f32 v103, v104, v105
	v_cvt_pk_bf16_f32 v104, v94, v95
	v_cvt_pk_bf16_f32 v105, v96, v97
	global_store_dwordx4 v[118:119], v[102:105], off offset:256 sc1
	s_and_saveexec_b64 s[14:15], s[40:41]
	s_cbranch_execz .LBB0_1038
	s_add_u32 s24, s6, s13
	s_addc_u32 s25, s7, s11
	v_lshl_add_u64 v[94:95], v[140:141], 1, s[24:25]
	global_store_dwordx4 v[94:95], v[102:105], off offset:256 sc1
.LBB0_1038:
	s_or_b64 exec, exec, s[14:15]
	v_or_b32_e32 v96, 32, v148
	v_mov_b64_e32 v[94:95], s[4:5]
	v_mad_i64_i32 v[94:95], s[14:15], v96, s26, v[94:95]
	v_lshl_add_u64 v[102:103], v[140:141], 1, v[94:95]
	v_ashrrev_i32_e32 v104, 4, v96
	v_cvt_pk_bf16_f32 v94, v98, v99
	v_cvt_pk_bf16_f32 v95, v100, v101
	v_cvt_pk_bf16_f32 v96, v90, v91
	v_cvt_pk_bf16_f32 v97, v92, v93
	global_store_dwordx4 v[102:103], v[94:97], off sc1
	s_and_saveexec_b64 s[14:15], s[42:43]
	s_cbranch_execz .LBB0_1040
	v_mov_b64_e32 v[90:91], s[6:7]
	v_mad_i64_i32 v[90:91], s[24:25], v104, s26, v[90:91]
	v_lshl_add_u64 v[90:91], v[140:141], 1, v[90:91]
	global_store_dwordx4 v[90:91], v[94:97], off sc1
.LBB0_1040:
	s_or_b64 exec, exec, s[14:15]
	v_cvt_pk_bf16_f32 v86, v86, v87
	v_cvt_pk_bf16_f32 v87, v88, v89
	v_cvt_pk_bf16_f32 v88, v78, v79
	v_cvt_pk_bf16_f32 v89, v80, v81
	global_store_dwordx4 v[102:103], v[86:89], off offset:256 sc1
	s_and_saveexec_b64 s[14:15], s[42:43]
	s_cbranch_execz .LBB0_1042
	v_mov_b64_e32 v[78:79], s[6:7]
	v_mad_i64_i32 v[78:79], s[24:25], v104, s26, v[78:79]
	v_lshl_add_u64 v[78:79], v[140:141], 1, v[78:79]
	global_store_dwordx4 v[78:79], v[86:89], off offset:256 sc1
.LBB0_1042:
	s_or_b64 exec, exec, s[14:15]
	v_or_b32_e32 v80, 48, v148
	v_mov_b64_e32 v[78:79], s[4:5]
	v_mad_i64_i32 v[78:79], s[14:15], v80, s26, v[78:79]
	v_lshl_add_u64 v[86:87], v[140:141], 1, v[78:79]
	v_ashrrev_i32_e32 v88, 4, v80
	v_cvt_pk_bf16_f32 v78, v82, v83
	v_cvt_pk_bf16_f32 v79, v84, v85
	v_cvt_pk_bf16_f32 v80, v74, v75
	v_cvt_pk_bf16_f32 v81, v76, v77
	global_store_dwordx4 v[86:87], v[78:81], off sc1
	s_and_saveexec_b64 s[14:15], s[40:41]
	s_cbranch_execz .LBB0_1044
	v_mov_b64_e32 v[74:75], s[6:7]
	v_mad_i64_i32 v[74:75], s[24:25], v88, s26, v[74:75]
	v_lshl_add_u64 v[74:75], v[140:141], 1, v[74:75]
	global_store_dwordx4 v[74:75], v[78:81], off sc1
.LBB0_1044:
	s_or_b64 exec, exec, s[14:15]
	v_cvt_pk_bf16_f32 v70, v70, v71
	v_cvt_pk_bf16_f32 v71, v72, v73
	v_cvt_pk_bf16_f32 v72, v66, v67
	v_cvt_pk_bf16_f32 v73, v68, v69
	global_store_dwordx4 v[86:87], v[70:73], off offset:256 sc1
	s_and_saveexec_b64 s[14:15], s[40:41]
	s_cbranch_execz .LBB0_1046
	v_mov_b64_e32 v[66:67], s[6:7]
	v_mad_i64_i32 v[66:67], s[24:25], v88, s26, v[66:67]
	v_lshl_add_u64 v[66:67], v[140:141], 1, v[66:67]
	global_store_dwordx4 v[66:67], v[70:73], off offset:256 sc1
.LBB0_1046:
	s_or_b64 exec, exec, s[14:15]
	v_add_u32_e32 v68, 0x80, v148
	v_mov_b64_e32 v[66:67], s[4:5]
	v_mad_i64_i32 v[66:67], s[14:15], v68, s26, v[66:67]
	v_lshl_add_u64 v[66:67], v[140:141], 1, v[66:67]
	v_ashrrev_i32_e32 v68, 4, v68
	v_cvt_pk_bf16_f32 v62, v62, v63
	v_cvt_pk_bf16_f32 v63, v64, v65
	v_cvt_pk_bf16_f32 v64, v58, v59
	v_cvt_pk_bf16_f32 v65, v60, v61
	global_store_dwordx4 v[66:67], v[62:65], off sc1
	s_and_saveexec_b64 s[14:15], s[42:43]
	s_cbranch_execz .LBB0_1048
	v_mov_b64_e32 v[58:59], s[6:7]
	v_mad_i64_i32 v[58:59], s[24:25], v68, s26, v[58:59]
	v_lshl_add_u64 v[58:59], v[140:141], 1, v[58:59]
	global_store_dwordx4 v[58:59], v[62:65], off sc1
.LBB0_1048:
	s_or_b64 exec, exec, s[14:15]
	v_cvt_pk_bf16_f32 v54, v54, v55
	v_cvt_pk_bf16_f32 v55, v56, v57
	v_cvt_pk_bf16_f32 v56, v46, v47
	v_cvt_pk_bf16_f32 v57, v48, v49
	global_store_dwordx4 v[66:67], v[54:57], off offset:256 sc1
	s_and_saveexec_b64 s[14:15], s[42:43]
	s_cbranch_execz .LBB0_1050
	v_mov_b64_e32 v[46:47], s[6:7]
	v_mad_i64_i32 v[46:47], s[24:25], v68, s26, v[46:47]
	v_lshl_add_u64 v[46:47], v[140:141], 1, v[46:47]
	global_store_dwordx4 v[46:47], v[54:57], off offset:256 sc1
.LBB0_1050:
	s_or_b64 exec, exec, s[14:15]
	v_add_u32_e32 v48, 0x90, v148
	v_mov_b64_e32 v[46:47], s[4:5]
	v_mad_i64_i32 v[46:47], s[14:15], v48, s26, v[46:47]
	v_lshl_add_u64 v[54:55], v[140:141], 1, v[46:47]
	v_ashrrev_i32_e32 v56, 4, v48
	v_cvt_pk_bf16_f32 v46, v50, v51
	v_cvt_pk_bf16_f32 v47, v52, v53
	v_cvt_pk_bf16_f32 v48, v42, v43
	v_cvt_pk_bf16_f32 v49, v44, v45
	global_store_dwordx4 v[54:55], v[46:49], off sc1
	s_and_saveexec_b64 s[14:15], s[40:41]
	s_cbranch_execz .LBB0_1052
	v_mov_b64_e32 v[42:43], s[6:7]
	v_mad_i64_i32 v[42:43], s[24:25], v56, s26, v[42:43]
	v_lshl_add_u64 v[42:43], v[140:141], 1, v[42:43]
	global_store_dwordx4 v[42:43], v[46:49], off sc1
.LBB0_1052:
	s_or_b64 exec, exec, s[14:15]
	v_cvt_pk_bf16_f32 v38, v38, v39
	v_cvt_pk_bf16_f32 v39, v40, v41
	v_cvt_pk_bf16_f32 v40, v30, v31
	v_cvt_pk_bf16_f32 v41, v32, v33
	global_store_dwordx4 v[54:55], v[38:41], off offset:256 sc1
	s_and_saveexec_b64 s[14:15], s[40:41]
	s_cbranch_execz .LBB0_1054
	v_mov_b64_e32 v[30:31], s[6:7]
	v_mad_i64_i32 v[30:31], s[24:25], v56, s26, v[30:31]
	v_lshl_add_u64 v[30:31], v[140:141], 1, v[30:31]
	global_store_dwordx4 v[30:31], v[38:41], off offset:256 sc1
.LBB0_1054:
	s_or_b64 exec, exec, s[14:15]
	v_add_u32_e32 v32, 0xa0, v148
	v_mov_b64_e32 v[30:31], s[4:5]
	v_mad_i64_i32 v[30:31], s[14:15], v32, s26, v[30:31]
	v_lshl_add_u64 v[38:39], v[140:141], 1, v[30:31]
	v_ashrrev_i32_e32 v40, 4, v32
	v_cvt_pk_bf16_f32 v30, v34, v35
	v_cvt_pk_bf16_f32 v31, v36, v37
	v_cvt_pk_bf16_f32 v32, v26, v27
	v_cvt_pk_bf16_f32 v33, v28, v29
	global_store_dwordx4 v[38:39], v[30:33], off sc1
	s_and_saveexec_b64 s[14:15], s[42:43]
	s_cbranch_execz .LBB0_1056
	v_mov_b64_e32 v[26:27], s[6:7]
	v_mad_i64_i32 v[26:27], s[24:25], v40, s26, v[26:27]
	v_lshl_add_u64 v[26:27], v[140:141], 1, v[26:27]
	global_store_dwordx4 v[26:27], v[30:33], off sc1
.LBB0_1056:
	s_or_b64 exec, exec, s[14:15]
	v_cvt_pk_bf16_f32 v22, v22, v23
	v_cvt_pk_bf16_f32 v23, v24, v25
	v_cvt_pk_bf16_f32 v24, v14, v15
	v_cvt_pk_bf16_f32 v25, v16, v17
	global_store_dwordx4 v[38:39], v[22:25], off offset:256 sc1
	s_and_saveexec_b64 s[14:15], s[42:43]
	s_cbranch_execz .LBB0_1058
	v_mov_b64_e32 v[14:15], s[6:7]
	v_mad_i64_i32 v[14:15], s[24:25], v40, s26, v[14:15]
	v_lshl_add_u64 v[14:15], v[140:141], 1, v[14:15]
	global_store_dwordx4 v[14:15], v[22:25], off offset:256 sc1
.LBB0_1058:
	s_or_b64 exec, exec, s[14:15]
	v_add_u32_e32 v16, 0xb0, v148
	v_mov_b64_e32 v[14:15], s[4:5]
	v_mad_i64_i32 v[14:15], s[14:15], v16, s26, v[14:15]
	v_lshl_add_u64 v[22:23], v[140:141], 1, v[14:15]
	v_ashrrev_i32_e32 v24, 4, v16
	v_cvt_pk_bf16_f32 v14, v18, v19
	v_cvt_pk_bf16_f32 v15, v20, v21
	v_cvt_pk_bf16_f32 v16, v10, v11
	v_cvt_pk_bf16_f32 v17, v12, v13
	global_store_dwordx4 v[22:23], v[14:17], off sc1
	s_and_saveexec_b64 s[14:15], s[40:41]
	s_cbranch_execz .LBB0_1060
	v_mov_b64_e32 v[10:11], s[6:7]
	v_mad_i64_i32 v[10:11], s[24:25], v24, s26, v[10:11]
	v_lshl_add_u64 v[10:11], v[140:141], 1, v[10:11]
	global_store_dwordx4 v[10:11], v[14:17], off sc1
.LBB0_1060:
	s_or_b64 exec, exec, s[14:15]
	v_cvt_pk_bf16_f32 v6, v6, v7
	v_cvt_pk_bf16_f32 v7, v8, v9
	v_cvt_pk_bf16_f32 v8, v2, v3
	v_cvt_pk_bf16_f32 v9, v4, v5
	global_store_dwordx4 v[22:23], v[6:9], off offset:256 sc1
	s_and_saveexec_b64 s[14:15], s[40:41]
	s_cbranch_execz .LBB0_1062
	v_mov_b64_e32 v[2:3], s[6:7]
	v_mad_i64_i32 v[2:3], s[24:25], v24, s26, v[2:3]
	v_lshl_add_u64 v[2:3], v[140:141], 1, v[2:3]
	global_store_dwordx4 v[2:3], v[6:9], off offset:256 sc1
